# v25: v24 + per-fragment K waits in the attention QK segment (no merged pair waits)
# baseline (speedup 1.0000x reference)
; #define MFMA(a, b, c) __builtin_amdgcn_mfma_f32_32x32x16_bf16((a), (b), (c), 0, 0, 0)
; __device__ __forceinline__ void at_partialSM(f32x16& p0, f32x16& p1, float& m_reg, float& alpha, bool force) {
;   float pm = p0[0];
; #pragma unroll
;   for (int r = 1; r < 16; ++r) pm = fmaxf(pm, p0[r]);
; #pragma unroll
;   for (int r = 0; r < 16; ++r) pm = fmaxf(pm, p1[r]);
;   { auto rr = __builtin_amdgcn_permlane32_swap(__float_as_uint(pm), __float_as_uint(pm), false, false);
;     pm = fmaxf(__uint_as_float(rr[0]), __uint_as_float(rr[1])); }
;   if (__builtin_expect(!force && __all(pm <= AT_THR * 1.4426950408889634f), 1)) { alpha = 1.f; }
;   else {
;     const float dlt = force ? pm : fmaxf(pm, 0.f);
;     alpha = force ? 1.f : __builtin_amdgcn_exp2f(-dlt); m_reg += dlt;
; #pragma unroll
;     for (int r = 0; r < 16; ++r) { p0[r] -= dlt; p1[r] -= dlt; }
; __device__ __forceinline__ void at_qkt(f32x16& p0, f32x16& p1, const char* Ks, const bf16x8* qr, int r32, int hi, float negm) {
; #pragma unroll
;   for (int r = 0; r < 16; ++r) { p0[r] = negm; p1[r] = negm; }
; #pragma unroll
;   for (int d0 = 0; d0 < 6; ++d0) {
;     const bf16x8 b0 = *(const bf16x8*)(Ks + r32 * AT_KROW + d0 * 32 + hi * 16);
;     const bf16x8 b1 = *(const bf16x8*)(Ks + (32 + r32) * AT_KROW + d0 * 32 + hi * 16);
;     p0 = MFMA(b0, qr[d0], p0);
;     p1 = MFMA(b1, qr[d0], p1);
;   }
; }
; __device__ void phase_attn(const Params& p, char* lds) {
;     ...
;     at_qkt(pA0, pA1, K_lds, qr, r32, hi, 0.f); at_partialSM(pA0, pA1, m_reg, alA, true);
.Lat_nostag:
	ds_read_b128 v[200:203], v170 offset:64
	ds_read_b128 v[204:207], v170 offset:6720
	s_waitcnt lgkmcnt(5)
	v_mfma_f32_32x32x16_bf16 v[32:47], v[184:187], v[80:83], 0
	s_waitcnt lgkmcnt(4)
	v_mfma_f32_32x32x16_bf16 v[48:63], v[188:191], v[80:83], 0
	ds_read_b128 v[208:211], v170 offset:96
	ds_read_b128 v[212:215], v170 offset:6752
	s_waitcnt lgkmcnt(5)
	v_mfma_f32_32x32x16_bf16 v[32:47], v[192:195], v[84:87], v[32:47]
	s_waitcnt lgkmcnt(4)
	v_mfma_f32_32x32x16_bf16 v[48:63], v[196:199], v[84:87], v[48:63]
	ds_read_b128 v[184:187], v170 offset:128
	ds_read_b128 v[188:191], v170 offset:6784
	s_waitcnt lgkmcnt(5)
	v_mfma_f32_32x32x16_bf16 v[32:47], v[200:203], v[88:91], v[32:47]
	s_waitcnt lgkmcnt(4)
	v_mfma_f32_32x32x16_bf16 v[48:63], v[204:207], v[88:91], v[48:63]
	ds_read_b128 v[192:195], v170 offset:160
	ds_read_b128 v[196:199], v170 offset:6816
	s_waitcnt lgkmcnt(5)
	v_mfma_f32_32x32x16_bf16 v[32:47], v[208:211], v[92:95], v[32:47]
	s_waitcnt lgkmcnt(4)
	v_mfma_f32_32x32x16_bf16 v[48:63], v[212:215], v[92:95], v[48:63]
	s_waitcnt lgkmcnt(3)
	v_mfma_f32_32x32x16_bf16 v[32:47], v[184:187], v[96:99], v[32:47]
	s_waitcnt lgkmcnt(2)
	v_mfma_f32_32x32x16_bf16 v[48:63], v[188:191], v[96:99], v[48:63]
	s_waitcnt lgkmcnt(1)
	v_mfma_f32_32x32x16_bf16 v[32:47], v[192:195], v[100:103], v[32:47]
	s_waitcnt lgkmcnt(0)
	v_mfma_f32_32x32x16_bf16 v[48:63], v[196:199], v[100:103], v[48:63]
	s_nop 11
	v_max3_f32 v174, v32, v33, v34
	v_max3_f32 v175, v48, v49, v50
	v_max3_f32 v174, v174, v35, v36
	v_max3_f32 v175, v175, v51, v52
	v_max3_f32 v174, v174, v37, v38
	v_max3_f32 v175, v175, v53, v54
	v_max3_f32 v174, v174, v39, v40
	v_max3_f32 v175, v175, v55, v56
	v_max3_f32 v174, v174, v41, v42
	v_max3_f32 v175, v175, v57, v58
	v_max3_f32 v174, v174, v43, v44
	v_max3_f32 v175, v175, v59, v60
	v_max3_f32 v174, v174, v45, v46
	v_max3_f32 v175, v175, v61, v62
	v_max3_f32 v174, v174, v47, v63
	v_max_f32_e32 v174, v174, v175
	v_mov_b32_e32 v175, v174
	s_nop 1
	v_permlane32_swap_b32_e32 v174, v175
	v_max_f32_e32 v174, v174, v175
	s_barrier
	v_mov_b32_e32 v172, v174
	v_sub_f32_e32 v32, v32, v174
	v_sub_f32_e32 v48, v48, v174
	v_sub_f32_e32 v33, v33, v174
	v_sub_f32_e32 v49, v49, v174
	v_sub_f32_e32 v34, v34, v174
	v_sub_f32_e32 v50, v50, v174
	v_sub_f32_e32 v35, v35, v174
	v_sub_f32_e32 v51, v51, v174
	v_sub_f32_e32 v36, v36, v174
	v_sub_f32_e32 v52, v52, v174
	v_sub_f32_e32 v37, v37, v174
	v_sub_f32_e32 v53, v53, v174
	v_sub_f32_e32 v38, v38, v174
	v_sub_f32_e32 v54, v54, v174
	v_sub_f32_e32 v39, v39, v174
	v_sub_f32_e32 v55, v55, v174
	v_sub_f32_e32 v40, v40, v174
	v_sub_f32_e32 v56, v56, v174
	v_sub_f32_e32 v41, v41, v174
	v_sub_f32_e32 v57, v57, v174
	v_sub_f32_e32 v42, v42, v174
	v_sub_f32_e32 v58, v58, v174
	v_sub_f32_e32 v43, v43, v174
	v_sub_f32_e32 v59, v59, v174
	v_sub_f32_e32 v44, v44, v174
	v_sub_f32_e32 v60, v60, v174
	v_sub_f32_e32 v45, v45, v174
	v_sub_f32_e32 v61, v61, v174
	v_sub_f32_e32 v46, v46, v174
	v_sub_f32_e32 v62, v62, v174
	v_sub_f32_e32 v47, v47, v174
	v_sub_f32_e32 v63, v63, v174
	v_sub_f32_e32 v64, 0, v174
	v_sub_f32_e32 v65, 0, v174
	v_sub_f32_e32 v66, 0, v174
	v_sub_f32_e32 v67, 0, v174
	v_sub_f32_e32 v68, 0, v174
	v_sub_f32_e32 v69, 0, v174
	v_sub_f32_e32 v70, 0, v174
	v_sub_f32_e32 v71, 0, v174
	v_sub_f32_e32 v72, 0, v174
	v_sub_f32_e32 v73, 0, v174
	v_sub_f32_e32 v74, 0, v174
	v_sub_f32_e32 v75, 0, v174
	v_sub_f32_e32 v76, 0, v174
	v_sub_f32_e32 v77, 0, v174
	v_sub_f32_e32 v78, 0, v174
	v_sub_f32_e32 v79, 0, v174
	s_add_i32 m0, s41, 0x19c00
	s_cmp_lt_u32 s14, 5
	global_load_lds_dwordx4 v246, s[86:87]
	v_add_u32_e32 v246, v248, v246
	s_cbranch_scc0 .Lat_kd4
	s_add_i32 m0, s30, 0x19c00
	s_nop 0
	global_load_lds_dwordx4 v250, s[86:87]

; __device__ __forceinline__ void at_qkt(f32x16& p0, f32x16& p1, const char* Ks, const bf16x8* qr, int r32, int hi, float negm) {
; #pragma unroll
;   for (int r = 0; r < 16; ++r) { p0[r] = negm; p1[r] = negm; }
; #pragma unroll
;   for (int d0 = 0; d0 < 6; ++d0) {
;     const bf16x8 b0 = *(const bf16x8*)(Ks + r32 * AT_KROW + d0 * 32 + hi * 16);
;     const bf16x8 b1 = *(const bf16x8*)(Ks + (32 + r32) * AT_KROW + d0 * 32 + hi * 16);
;     p0 = MFMA(b0, qr[d0], p0);
;     p1 = MFMA(b1, qr[d0], p1);
;   }
; }
; __device__ __forceinline__ int v_st(int k, int c) { const int kk = (k & ~0xC) | ((k & 4) << 1) | ((k & 8) >> 1); return ((kk >> 3) * 4 + (c >> 5)) * 512 + ((kk & 7) * 32 + (c & 31)) * 2; }
; __device__ __forceinline__ int v_rd_base(int lane) { return ((lane & 3) << 3) | (((lane >> 2) & 3) << 6) | (((lane >> 4) & 1) << 5) | (((lane >> 5) & 1) << 8); }
; template <int OFF> __device__ __forceinline__ s16x4 tr_read(int vb) {
;   s16x4 r; asm volatile("ds_read_b64_tr_b16 %0, %1 offset:%2" : "=&v"(r) : "v"(vb), "i"(OFF) : "memory"); return r;
; }
; template <int D0> __device__ __forceinline__ void pv_one(f32x16& od, int vb, bf16x8 pa0, bf16x8 pa1, bf16x8 pa2, bf16x8 pa3) {
;   const s16x4 l0 = tr_read<v_rd_off(D0, 0, 0)>(vb), h0 = tr_read<v_rd_off(D0, 0, 1)>(vb), l1 = tr_read<v_rd_off(D0, 1, 0)>(vb), h1 = tr_read<v_rd_off(D0, 1, 1)>(vb);
;   const s16x4 l2 = tr_read<v_rd_off(D0, 2, 0)>(vb), h2 = tr_read<v_rd_off(D0, 2, 1)>(vb), l3 = tr_read<v_rd_off(D0, 3, 0)>(vb), h3 = tr_read<v_rd_off(D0, 3, 1)>(vb);
;   asm volatile("s_waitcnt lgkmcnt(0)" ::: "memory"); SBAR();
;     ...
;   od = MFMA(pa0, PK(l0, h0), od);
;   od = MFMA(pa1, PK(l1, h1), od);
;   od = MFMA(pa2, PK(l2, h2), od);
;   od = MFMA(pa3, PK(l3, h3), od);
;     ...
; }
; __device__ __forceinline__ void pv_d0(f32x16* o, int vb, bf16x8 pa0, bf16x8 pa1, bf16x8 pa2, bf16x8 pa3) {
;   pv_one<0>(o[0], vb, pa0, pa1, pa2, pa3); pv_one<1>(o[1], vb, pa0, pa1, pa2, pa3);
; }
; __device__ void phase_attn(const Params& p, char* lds) {
;     ...
;     for (int j = 1; j + 1 < NT; j += 2) {
;       SBAR(); at_qkt(pB0, pB1, K_lds + AT_SHMK, qr, r32, hi, -m_reg);
;       at_finishSM(pA0, pA1, alA, l_reg, pa0, pa1, pa2, pa3); SBAR();
;       SLOAD(1, (j + 2) * 64); SBAR();
;       pv_d0(o, vb0, pa0, pa1, pa2, pa3); at_partialSM(pB0, pB1, m_reg, alB, false);
;       __syncthreads(); SWAIT(); SWRITE(0, 0);
;       RESC(alB); __syncthreads();
.Lat_loop:
	ds_read_b128 v[200:203], v170 offset:13376
	ds_read_b128 v[204:207], v170 offset:20032
	s_waitcnt lgkmcnt(5)
	v_mfma_f32_32x32x16_bf16 v[32:47], v[184:187], v[80:83], v[64:79]
	s_waitcnt lgkmcnt(4)
	v_mfma_f32_32x32x16_bf16 v[48:63], v[188:191], v[80:83], v[64:79]
	ds_read_b128 v[208:211], v170 offset:13408
	ds_read_b128 v[212:215], v170 offset:20064
	s_waitcnt lgkmcnt(5)
	v_mfma_f32_32x32x16_bf16 v[32:47], v[192:195], v[84:87], v[32:47]
	s_waitcnt lgkmcnt(4)
	v_mfma_f32_32x32x16_bf16 v[48:63], v[196:199], v[84:87], v[48:63]
	ds_read_b128 v[184:187], v170 offset:13440
	ds_read_b128 v[188:191], v170 offset:20096
	s_waitcnt lgkmcnt(5)
	v_mfma_f32_32x32x16_bf16 v[32:47], v[200:203], v[88:91], v[32:47]
	s_waitcnt lgkmcnt(4)
	v_mfma_f32_32x32x16_bf16 v[48:63], v[204:207], v[88:91], v[48:63]
	ds_read_b128 v[192:195], v170 offset:13472
	ds_read_b128 v[196:199], v170 offset:20128
	s_waitcnt lgkmcnt(5)
	v_mfma_f32_32x32x16_bf16 v[32:47], v[208:211], v[92:95], v[32:47]
	s_waitcnt lgkmcnt(4)
	v_mfma_f32_32x32x16_bf16 v[48:63], v[212:215], v[92:95], v[48:63]
	ds_read_b64_tr_b16 v[148:149], v171 offset:0
	ds_read_b64_tr_b16 v[150:151], v171 offset:2048
	ds_read_b64_tr_b16 v[152:153], v171 offset:4096
	ds_read_b64_tr_b16 v[154:155], v171 offset:6144
	s_waitcnt lgkmcnt(7)
	v_mfma_f32_32x32x16_bf16 v[32:47], v[184:187], v[96:99], v[32:47]
	s_waitcnt lgkmcnt(6)
	v_mfma_f32_32x32x16_bf16 v[48:63], v[188:191], v[96:99], v[48:63]
	ds_read_b64_tr_b16 v[156:157], v171 offset:8192
	ds_read_b64_tr_b16 v[158:159], v171 offset:10240
	ds_read_b64_tr_b16 v[216:217], v171 offset:12288
	ds_read_b64_tr_b16 v[218:219], v171 offset:14336
	s_waitcnt lgkmcnt(9)
	v_mfma_f32_32x32x16_bf16 v[32:47], v[192:195], v[100:103], v[32:47]
	s_waitcnt lgkmcnt(8)
	v_mfma_f32_32x32x16_bf16 v[48:63], v[196:199], v[100:103], v[48:63]
	ds_read_b64_tr_b16 v[220:221], v171 offset:512
	ds_read_b64_tr_b16 v[222:223], v171 offset:2560
	ds_read_b64_tr_b16 v[224:225], v171 offset:4608
	ds_read_b64_tr_b16 v[226:227], v171 offset:6656
	s_waitcnt lgkmcnt(10)
	v_mfma_f32_32x32x16_bf16 v[0:15], v[104:107], v[148:151], v[0:15]
	s_waitcnt lgkmcnt(8)
	v_mfma_f32_32x32x16_bf16 v[0:15], v[108:111], v[152:155], v[0:15]
	ds_read_b64_tr_b16 v[236:237], v171 offset:8704
	ds_read_b64_tr_b16 v[238:239], v171 offset:10752
	ds_read_b64_tr_b16 v[240:241], v171 offset:12800
	ds_read_b64_tr_b16 v[242:243], v171 offset:14848
	s_waitcnt lgkmcnt(10)
	v_mfma_f32_32x32x16_bf16 v[0:15], v[112:115], v[156:159], v[0:15]
	s_waitcnt lgkmcnt(8)
	v_mfma_f32_32x32x16_bf16 v[0:15], v[116:119], v[216:219], v[0:15]
	s_waitcnt lgkmcnt(6)
	v_mfma_f32_32x32x16_bf16 v[16:31], v[104:107], v[220:223], v[16:31]
	s_waitcnt lgkmcnt(4)
	v_mfma_f32_32x32x16_bf16 v[16:31], v[108:111], v[224:227], v[16:31]
	s_waitcnt lgkmcnt(2)
	v_mfma_f32_32x32x16_bf16 v[16:31], v[112:115], v[236:239], v[16:31]
	s_waitcnt lgkmcnt(0)
	v_mfma_f32_32x32x16_bf16 v[16:31], v[116:119], v[240:243], v[16:31]
	s_barrier
	s_waitcnt vmcnt(0)
	s_add_i32 m0, s41, 0x10000
	s_cmp_lt_u32 s14, 5
	global_load_lds_dwordx4 v246, s[86:87]
	v_add_u32_e32 v246, v248, v246
	s_cbranch_scc0 .Lat_kd5
	s_add_i32 m0, s30, 0x10000
	s_nop 0
	global_load_lds_dwordx4 v250, s[86:87]

; __device__ __forceinline__ void at_finishSM(f32x16& p0, f32x16& p1, float alpha, float& l_reg, bf16x8& pa0, bf16x8& pa1, bf16x8& pa2, bf16x8& pa3) {
; #pragma unroll
;   for (int r = 0; r < 16; ++r) p1[r] = __builtin_amdgcn_exp2f(p1[r]);
;   float ps = 0;
; #pragma unroll
;   for (int r = 0; r < 16; ++r) ps += p0[r];
; #pragma unroll
;   for (int r = 0; r < 16; ++r) ps += p1[r];
;   { auto rr = __builtin_amdgcn_permlane32_swap(__float_as_uint(ps), __float_as_uint(ps), false, false);
;     ps = __uint_as_float(rr[0]) + __uint_as_float(rr[1]); }
;   l_reg = l_reg * alpha + ps;
;     ...
;   PK4(p0, 0, pa0); PK4(p0, 8, pa1); PK4(p1, 0, pa2); PK4(p1, 8, pa3);
;     ...
; }
; __device__ __forceinline__ void at_qkt(f32x16& p0, f32x16& p1, const char* Ks, const bf16x8* qr, int r32, int hi, float negm) {
; #pragma unroll
;   for (int r = 0; r < 16; ++r) { p0[r] = negm; p1[r] = negm; }
; #pragma unroll
;   for (int d0 = 0; d0 < 6; ++d0) {
;     const bf16x8 b0 = *(const bf16x8*)(Ks + r32 * AT_KROW + d0 * 32 + hi * 16);
;     const bf16x8 b1 = *(const bf16x8*)(Ks + (32 + r32) * AT_KROW + d0 * 32 + hi * 16);
;     p0 = MFMA(b0, qr[d0], p0);
;     p1 = MFMA(b1, qr[d0], p1);
;   }
; }
; __device__ __forceinline__ int v_st(int k, int c) { const int kk = (k & ~0xC) | ((k & 4) << 1) | ((k & 8) >> 1); return ((kk >> 3) * 4 + (c >> 5)) * 512 + ((kk & 7) * 32 + (c & 31)) * 2; }
; __device__ __forceinline__ int v_rd_base(int lane) { return ((lane & 3) << 3) | (((lane >> 2) & 3) << 6) | (((lane >> 4) & 1) << 5) | (((lane >> 5) & 1) << 8); }
; __device__ void phase_attn(const Params& p, char* lds) {
;     ...
;     for (int j = 1; j + 1 < NT; j += 2) {
;       SBAR(); at_qkt(pB0, pB1, K_lds + AT_SHMK, qr, r32, hi, -m_reg);
;       at_finishSM(pA0, pA1, alA, l_reg, pa0, pa1, pa2, pa3); SBAR();
;       SLOAD(1, (j + 2) * 64); SBAR();
;       pv_d0(o, vb0, pa0, pa1, pa2, pa3); at_partialSM(pB0, pB1, m_reg, alB, false);
;       __syncthreads(); SWAIT(); SWRITE(0, 0);
;       RESC(alB); __syncthreads();
;       SBAR(); at_qkt(pA0, pA1, K_lds, qr, r32, hi, -m_reg);
;       at_finishSM(pB0, pB1, alB, l_reg, pa0, pa1, pa2, pa3); SBAR();
;       if (j + 3 < NT) SLOAD(0, (j + 3) * 64); SBAR();
;       pv_d0(o, vb0 + AT_SHMV, pa0, pa1, pa2, pa3); at_partialSM(pA0, pA1, m_reg, alA, false);
;       __syncthreads(); SWAIT(); SWRITE(1, 1);
;       RESC(alA); __syncthreads();
.Lat_rare0_back:
	v_add_f32_e32 v173, v173, v175
	v_cvt_pk_bf16_f32 v104, v32, v33
	v_cvt_pk_bf16_f32 v105, v34, v35
	v_cvt_pk_bf16_f32 v106, v36, v37
	v_cvt_pk_bf16_f32 v107, v38, v39
	v_cvt_pk_bf16_f32 v108, v40, v41
	v_cvt_pk_bf16_f32 v109, v42, v43
	v_cvt_pk_bf16_f32 v110, v44, v45
	v_cvt_pk_bf16_f32 v111, v46, v47
	v_cvt_pk_bf16_f32 v112, v48, v49
	v_cvt_pk_bf16_f32 v113, v50, v51
	v_cvt_pk_bf16_f32 v114, v52, v53
	v_cvt_pk_bf16_f32 v115, v54, v55
	v_cvt_pk_bf16_f32 v116, v56, v57
	v_cvt_pk_bf16_f32 v117, v58, v59
	v_cvt_pk_bf16_f32 v118, v60, v61
	v_cvt_pk_bf16_f32 v119, v62, v63
	ds_read_b128 v[184:187], v170 offset:26624
	ds_read_b128 v[188:191], v170 offset:33280
	ds_read_b128 v[192:195], v170 offset:26656
	ds_read_b128 v[196:199], v170 offset:33312
	s_barrier
	ds_read_b128 v[200:203], v170 offset:26688
	ds_read_b128 v[204:207], v170 offset:33344
	s_waitcnt lgkmcnt(5)
	v_mfma_f32_32x32x16_bf16 v[32:47], v[184:187], v[80:83], v[64:79]
	s_waitcnt lgkmcnt(4)
	v_mfma_f32_32x32x16_bf16 v[48:63], v[188:191], v[80:83], v[64:79]
	ds_read_b128 v[208:211], v170 offset:26720
	ds_read_b128 v[212:215], v170 offset:33376
	s_waitcnt lgkmcnt(5)
	v_mfma_f32_32x32x16_bf16 v[32:47], v[192:195], v[84:87], v[32:47]
	s_waitcnt lgkmcnt(4)
	v_mfma_f32_32x32x16_bf16 v[48:63], v[196:199], v[84:87], v[48:63]
	ds_read_b128 v[184:187], v170 offset:26752
	ds_read_b128 v[188:191], v170 offset:33408
	s_waitcnt lgkmcnt(5)
	v_mfma_f32_32x32x16_bf16 v[32:47], v[200:203], v[88:91], v[32:47]
	s_waitcnt lgkmcnt(4)
	v_mfma_f32_32x32x16_bf16 v[48:63], v[204:207], v[88:91], v[48:63]
	ds_read_b128 v[192:195], v170 offset:26784
	ds_read_b128 v[196:199], v170 offset:33440
	s_waitcnt lgkmcnt(5)
	v_mfma_f32_32x32x16_bf16 v[32:47], v[208:211], v[92:95], v[32:47]
	s_waitcnt lgkmcnt(4)
	v_mfma_f32_32x32x16_bf16 v[48:63], v[212:215], v[92:95], v[48:63]
	ds_read_b64_tr_b16 v[148:149], v171 offset:16384
	ds_read_b64_tr_b16 v[150:151], v171 offset:18432
	ds_read_b64_tr_b16 v[152:153], v171 offset:20480
	ds_read_b64_tr_b16 v[154:155], v171 offset:22528
	s_waitcnt lgkmcnt(7)
	v_mfma_f32_32x32x16_bf16 v[32:47], v[184:187], v[96:99], v[32:47]
	s_waitcnt lgkmcnt(6)
	v_mfma_f32_32x32x16_bf16 v[48:63], v[188:191], v[96:99], v[48:63]
	ds_read_b64_tr_b16 v[156:157], v171 offset:24576
	ds_read_b64_tr_b16 v[158:159], v171 offset:26624
	ds_read_b64_tr_b16 v[216:217], v171 offset:28672
	ds_read_b64_tr_b16 v[218:219], v171 offset:30720
	s_waitcnt lgkmcnt(9)
	v_mfma_f32_32x32x16_bf16 v[32:47], v[192:195], v[100:103], v[32:47]
	s_waitcnt lgkmcnt(8)
	v_mfma_f32_32x32x16_bf16 v[48:63], v[196:199], v[100:103], v[48:63]
	ds_read_b64_tr_b16 v[220:221], v171 offset:16896
	ds_read_b64_tr_b16 v[222:223], v171 offset:18944
	ds_read_b64_tr_b16 v[224:225], v171 offset:20992
	ds_read_b64_tr_b16 v[226:227], v171 offset:23040
	s_waitcnt lgkmcnt(10)
	v_mfma_f32_32x32x16_bf16 v[0:15], v[104:107], v[148:151], v[0:15]
	s_waitcnt lgkmcnt(8)
	v_mfma_f32_32x32x16_bf16 v[0:15], v[108:111], v[152:155], v[0:15]
	ds_read_b64_tr_b16 v[236:237], v171 offset:25088
	ds_read_b64_tr_b16 v[238:239], v171 offset:27136
	ds_read_b64_tr_b16 v[240:241], v171 offset:29184
	ds_read_b64_tr_b16 v[242:243], v171 offset:31232
	s_waitcnt lgkmcnt(10)
	v_mfma_f32_32x32x16_bf16 v[0:15], v[112:115], v[156:159], v[0:15]
	s_waitcnt lgkmcnt(8)
	v_mfma_f32_32x32x16_bf16 v[0:15], v[116:119], v[216:219], v[0:15]
	s_waitcnt lgkmcnt(6)
	v_mfma_f32_32x32x16_bf16 v[16:31], v[104:107], v[220:223], v[16:31]
	s_waitcnt lgkmcnt(4)
	v_mfma_f32_32x32x16_bf16 v[16:31], v[108:111], v[224:227], v[16:31]
	s_waitcnt lgkmcnt(2)
	v_mfma_f32_32x32x16_bf16 v[16:31], v[112:115], v[236:239], v[16:31]
	s_waitcnt lgkmcnt(0)
	v_mfma_f32_32x32x16_bf16 v[16:31], v[116:119], v[240:243], v[16:31]
	s_barrier
	s_waitcnt vmcnt(0)
	s_add_i32 m0, s41, 0x13400
	s_cmp_lt_u32 s14, 5
	global_load_lds_dwordx4 v246, s[86:87]
	v_add_u32_e32 v246, v248, v246
	s_cbranch_scc0 .Lat_kd6
	s_add_i32 m0, s30, 0x13400
	s_nop 0
	global_load_lds_dwordx4 v250, s[86:87]

; __device__ __forceinline__ void at_finishSM(f32x16& p0, f32x16& p1, float alpha, float& l_reg, bf16x8& pa0, bf16x8& pa1, bf16x8& pa2, bf16x8& pa3) {
; #pragma unroll
;   for (int r = 0; r < 16; ++r) p1[r] = __builtin_amdgcn_exp2f(p1[r]);
;   float ps = 0;
; #pragma unroll
;   for (int r = 0; r < 16; ++r) ps += p0[r];
; #pragma unroll
;   for (int r = 0; r < 16; ++r) ps += p1[r];
;   { auto rr = __builtin_amdgcn_permlane32_swap(__float_as_uint(ps), __float_as_uint(ps), false, false);
;     ps = __uint_as_float(rr[0]) + __uint_as_float(rr[1]); }
;   l_reg = l_reg * alpha + ps;
;     ...
;   PK4(p0, 0, pa0); PK4(p0, 8, pa1); PK4(p1, 0, pa2); PK4(p1, 8, pa3);
;     ...
; }
; __device__ __forceinline__ void at_qkt(f32x16& p0, f32x16& p1, const char* Ks, const bf16x8* qr, int r32, int hi, float negm) {
; #pragma unroll
;   for (int r = 0; r < 16; ++r) { p0[r] = negm; p1[r] = negm; }
; #pragma unroll
;   for (int d0 = 0; d0 < 6; ++d0) {
;     const bf16x8 b0 = *(const bf16x8*)(Ks + r32 * AT_KROW + d0 * 32 + hi * 16);
;     const bf16x8 b1 = *(const bf16x8*)(Ks + (32 + r32) * AT_KROW + d0 * 32 + hi * 16);
;     p0 = MFMA(b0, qr[d0], p0);
;     p1 = MFMA(b1, qr[d0], p1);
;   }
; }
; __device__ __forceinline__ int v_st(int k, int c) { const int kk = (k & ~0xC) | ((k & 4) << 1) | ((k & 8) >> 1); return ((kk >> 3) * 4 + (c >> 5)) * 512 + ((kk & 7) * 32 + (c & 31)) * 2; }
; __device__ __forceinline__ int v_rd_base(int lane) { return ((lane & 3) << 3) | (((lane >> 2) & 3) << 6) | (((lane >> 4) & 1) << 5) | (((lane >> 5) & 1) << 8); }
; __device__ void phase_attn(const Params& p, char* lds) {
;     ...
;     for (int j = 1; j + 1 < NT; j += 2) {
;       SBAR(); at_qkt(pB0, pB1, K_lds + AT_SHMK, qr, r32, hi, -m_reg);
;       at_finishSM(pA0, pA1, alA, l_reg, pa0, pa1, pa2, pa3); SBAR();
;       SLOAD(1, (j + 2) * 64); SBAR();
;       pv_d0(o, vb0, pa0, pa1, pa2, pa3); at_partialSM(pB0, pB1, m_reg, alB, false);
;       __syncthreads(); SWAIT(); SWRITE(0, 0);
;       RESC(alB); __syncthreads();
;       SBAR(); at_qkt(pA0, pA1, K_lds, qr, r32, hi, -m_reg);
;       at_finishSM(pB0, pB1, alB, l_reg, pa0, pa1, pa2, pa3); SBAR();
;       if (j + 3 < NT) SLOAD(0, (j + 3) * 64); SBAR();
;       pv_d0(o, vb0 + AT_SHMV, pa0, pa1, pa2, pa3); at_partialSM(pA0, pA1, m_reg, alA, false);
;       __syncthreads(); SWAIT(); SWRITE(1, 1);
;       RESC(alA); __syncthreads();
.Lat_rare1_back:
	v_add_f32_e32 v173, v173, v175
	v_cvt_pk_bf16_f32 v104, v32, v33
	v_cvt_pk_bf16_f32 v105, v34, v35
	v_cvt_pk_bf16_f32 v106, v36, v37
	v_cvt_pk_bf16_f32 v107, v38, v39
	v_cvt_pk_bf16_f32 v108, v40, v41
	v_cvt_pk_bf16_f32 v109, v42, v43
	v_cvt_pk_bf16_f32 v110, v44, v45
	v_cvt_pk_bf16_f32 v111, v46, v47
	v_cvt_pk_bf16_f32 v112, v48, v49
	v_cvt_pk_bf16_f32 v113, v50, v51
	v_cvt_pk_bf16_f32 v114, v52, v53
	v_cvt_pk_bf16_f32 v115, v54, v55
	v_cvt_pk_bf16_f32 v116, v56, v57
	v_cvt_pk_bf16_f32 v117, v58, v59
	v_cvt_pk_bf16_f32 v118, v60, v61
	v_cvt_pk_bf16_f32 v119, v62, v63
	ds_read_b128 v[184:187], v170 offset:39936
	ds_read_b128 v[188:191], v170 offset:46592
	ds_read_b128 v[192:195], v170 offset:39968
	ds_read_b128 v[196:199], v170 offset:46624
	s_barrier
	ds_read_b128 v[200:203], v170 offset:40000
	ds_read_b128 v[204:207], v170 offset:46656
	s_waitcnt lgkmcnt(5)
	v_mfma_f32_32x32x16_bf16 v[32:47], v[184:187], v[80:83], v[64:79]
	s_waitcnt lgkmcnt(4)
	v_mfma_f32_32x32x16_bf16 v[48:63], v[188:191], v[80:83], v[64:79]
	ds_read_b128 v[208:211], v170 offset:40032
	ds_read_b128 v[212:215], v170 offset:46688
	s_waitcnt lgkmcnt(5)
	v_mfma_f32_32x32x16_bf16 v[32:47], v[192:195], v[84:87], v[32:47]
	s_waitcnt lgkmcnt(4)
	v_mfma_f32_32x32x16_bf16 v[48:63], v[196:199], v[84:87], v[48:63]
	ds_read_b128 v[184:187], v170 offset:40064
	ds_read_b128 v[188:191], v170 offset:46720
	s_waitcnt lgkmcnt(5)
	v_mfma_f32_32x32x16_bf16 v[32:47], v[200:203], v[88:91], v[32:47]
	s_waitcnt lgkmcnt(4)
	v_mfma_f32_32x32x16_bf16 v[48:63], v[204:207], v[88:91], v[48:63]
	ds_read_b128 v[192:195], v170 offset:40096
	ds_read_b128 v[196:199], v170 offset:46752
	s_waitcnt lgkmcnt(5)
	v_mfma_f32_32x32x16_bf16 v[32:47], v[208:211], v[92:95], v[32:47]
	s_waitcnt lgkmcnt(4)
	v_mfma_f32_32x32x16_bf16 v[48:63], v[212:215], v[92:95], v[48:63]
	ds_read_b64_tr_b16 v[148:149], v171 offset:32768
	ds_read_b64_tr_b16 v[150:151], v171 offset:34816
	ds_read_b64_tr_b16 v[152:153], v171 offset:36864
	ds_read_b64_tr_b16 v[154:155], v171 offset:38912
	s_waitcnt lgkmcnt(7)
	v_mfma_f32_32x32x16_bf16 v[32:47], v[184:187], v[96:99], v[32:47]
	s_waitcnt lgkmcnt(6)
	v_mfma_f32_32x32x16_bf16 v[48:63], v[188:191], v[96:99], v[48:63]
	ds_read_b64_tr_b16 v[156:157], v171 offset:40960
	ds_read_b64_tr_b16 v[158:159], v171 offset:43008
	ds_read_b64_tr_b16 v[216:217], v171 offset:45056
	ds_read_b64_tr_b16 v[218:219], v171 offset:47104
	s_waitcnt lgkmcnt(9)
	v_mfma_f32_32x32x16_bf16 v[32:47], v[192:195], v[100:103], v[32:47]
	s_waitcnt lgkmcnt(8)
	v_mfma_f32_32x32x16_bf16 v[48:63], v[196:199], v[100:103], v[48:63]
	ds_read_b64_tr_b16 v[220:221], v171 offset:33280
	ds_read_b64_tr_b16 v[222:223], v171 offset:35328
	ds_read_b64_tr_b16 v[224:225], v171 offset:37376
	ds_read_b64_tr_b16 v[226:227], v171 offset:39424
	s_waitcnt lgkmcnt(10)
	v_mfma_f32_32x32x16_bf16 v[0:15], v[104:107], v[148:151], v[0:15]
	s_waitcnt lgkmcnt(8)
	v_mfma_f32_32x32x16_bf16 v[0:15], v[108:111], v[152:155], v[0:15]
	ds_read_b64_tr_b16 v[236:237], v171 offset:41472
	ds_read_b64_tr_b16 v[238:239], v171 offset:43520
	ds_read_b64_tr_b16 v[240:241], v171 offset:45568
	ds_read_b64_tr_b16 v[242:243], v171 offset:47616
	s_waitcnt lgkmcnt(10)
	v_mfma_f32_32x32x16_bf16 v[0:15], v[112:115], v[156:159], v[0:15]
	s_waitcnt lgkmcnt(8)
	v_mfma_f32_32x32x16_bf16 v[0:15], v[116:119], v[216:219], v[0:15]
	s_waitcnt lgkmcnt(6)
	v_mfma_f32_32x32x16_bf16 v[16:31], v[104:107], v[220:223], v[16:31]
	s_waitcnt lgkmcnt(4)
	v_mfma_f32_32x32x16_bf16 v[16:31], v[108:111], v[224:227], v[16:31]
	s_waitcnt lgkmcnt(2)
	v_mfma_f32_32x32x16_bf16 v[16:31], v[112:115], v[236:239], v[16:31]
	s_waitcnt lgkmcnt(0)
	v_mfma_f32_32x32x16_bf16 v[16:31], v[116:119], v[240:243], v[16:31]
	s_barrier
	s_waitcnt vmcnt(0)
	s_add_i32 m0, s41, 0x16800
	s_cmp_lt_u32 s14, 5
	global_load_lds_dwordx4 v246, s[86:87]
	v_add_u32_e32 v246, v248, v246
	s_cbranch_scc0 .Lat_kd7
	s_add_i32 m0, s30, 0x16800
	s_nop 0
	global_load_lds_dwordx4 v250, s[86:87]

; __device__ __forceinline__ void at_finishSM(f32x16& p0, f32x16& p1, float alpha, float& l_reg, bf16x8& pa0, bf16x8& pa1, bf16x8& pa2, bf16x8& pa3) {
; #pragma unroll
;   for (int r = 0; r < 16; ++r) p1[r] = __builtin_amdgcn_exp2f(p1[r]);
;   float ps = 0;
; #pragma unroll
;   for (int r = 0; r < 16; ++r) ps += p0[r];
; #pragma unroll
;   for (int r = 0; r < 16; ++r) ps += p1[r];
;   { auto rr = __builtin_amdgcn_permlane32_swap(__float_as_uint(ps), __float_as_uint(ps), false, false);
;     ps = __uint_as_float(rr[0]) + __uint_as_float(rr[1]); }
;   l_reg = l_reg * alpha + ps;
;     ...
;   PK4(p0, 0, pa0); PK4(p0, 8, pa1); PK4(p1, 0, pa2); PK4(p1, 8, pa3);
;     ...
; }
; __device__ __forceinline__ void at_qkt(f32x16& p0, f32x16& p1, const char* Ks, const bf16x8* qr, int r32, int hi, float negm) {
; #pragma unroll
;   for (int r = 0; r < 16; ++r) { p0[r] = negm; p1[r] = negm; }
; #pragma unroll
;   for (int d0 = 0; d0 < 6; ++d0) {
;     const bf16x8 b0 = *(const bf16x8*)(Ks + r32 * AT_KROW + d0 * 32 + hi * 16);
;     const bf16x8 b1 = *(const bf16x8*)(Ks + (32 + r32) * AT_KROW + d0 * 32 + hi * 16);
;     p0 = MFMA(b0, qr[d0], p0);
;     p1 = MFMA(b1, qr[d0], p1);
;   }
; }
; __device__ __forceinline__ int v_st(int k, int c) { const int kk = (k & ~0xC) | ((k & 4) << 1) | ((k & 8) >> 1); return ((kk >> 3) * 4 + (c >> 5)) * 512 + ((kk & 7) * 32 + (c & 31)) * 2; }
; __device__ __forceinline__ int v_rd_base(int lane) { return ((lane & 3) << 3) | (((lane >> 2) & 3) << 6) | (((lane >> 4) & 1) << 5) | (((lane >> 5) & 1) << 8); }
; __device__ void phase_attn(const Params& p, char* lds) {
;     ...
;     for (int j = 1; j + 1 < NT; j += 2) {
;       SBAR(); at_qkt(pB0, pB1, K_lds + AT_SHMK, qr, r32, hi, -m_reg);
;       at_finishSM(pA0, pA1, alA, l_reg, pa0, pa1, pa2, pa3); SBAR();
;       SLOAD(1, (j + 2) * 64); SBAR();
;       pv_d0(o, vb0, pa0, pa1, pa2, pa3); at_partialSM(pB0, pB1, m_reg, alB, false);
;       __syncthreads(); SWAIT(); SWRITE(0, 0);
;       RESC(alB); __syncthreads();
;       SBAR(); at_qkt(pA0, pA1, K_lds, qr, r32, hi, -m_reg);
;       at_finishSM(pB0, pB1, alB, l_reg, pa0, pa1, pa2, pa3); SBAR();
;       if (j + 3 < NT) SLOAD(0, (j + 3) * 64); SBAR();
;       pv_d0(o, vb0 + AT_SHMV, pa0, pa1, pa2, pa3); at_partialSM(pA0, pA1, m_reg, alA, false);
;       __syncthreads(); SWAIT(); SWRITE(1, 1);
;       RESC(alA); __syncthreads();
.Lat_rare2_back:
	v_add_f32_e32 v173, v173, v175
	v_cvt_pk_bf16_f32 v104, v32, v33
	v_cvt_pk_bf16_f32 v105, v34, v35
	v_cvt_pk_bf16_f32 v106, v36, v37
	v_cvt_pk_bf16_f32 v107, v38, v39
	v_cvt_pk_bf16_f32 v108, v40, v41
	v_cvt_pk_bf16_f32 v109, v42, v43
	v_cvt_pk_bf16_f32 v110, v44, v45
	v_cvt_pk_bf16_f32 v111, v46, v47
	v_cvt_pk_bf16_f32 v112, v48, v49
	v_cvt_pk_bf16_f32 v113, v50, v51
	v_cvt_pk_bf16_f32 v114, v52, v53
	v_cvt_pk_bf16_f32 v115, v54, v55
	v_cvt_pk_bf16_f32 v116, v56, v57
	v_cvt_pk_bf16_f32 v117, v58, v59
	v_cvt_pk_bf16_f32 v118, v60, v61
	v_cvt_pk_bf16_f32 v119, v62, v63
	ds_read_b128 v[184:187], v170 offset:0
	ds_read_b128 v[188:191], v170 offset:6656
	ds_read_b128 v[192:195], v170 offset:32
	ds_read_b128 v[196:199], v170 offset:6688
	s_barrier
	ds_read_b128 v[200:203], v170 offset:64
	ds_read_b128 v[204:207], v170 offset:6720
	s_waitcnt lgkmcnt(5)
	v_mfma_f32_32x32x16_bf16 v[32:47], v[184:187], v[80:83], v[64:79]
	s_waitcnt lgkmcnt(4)
	v_mfma_f32_32x32x16_bf16 v[48:63], v[188:191], v[80:83], v[64:79]
	ds_read_b128 v[208:211], v170 offset:96
	ds_read_b128 v[212:215], v170 offset:6752
	s_waitcnt lgkmcnt(5)
	v_mfma_f32_32x32x16_bf16 v[32:47], v[192:195], v[84:87], v[32:47]
	s_waitcnt lgkmcnt(4)
	v_mfma_f32_32x32x16_bf16 v[48:63], v[196:199], v[84:87], v[48:63]
	ds_read_b128 v[184:187], v170 offset:128
	ds_read_b128 v[188:191], v170 offset:6784
	s_waitcnt lgkmcnt(5)
	v_mfma_f32_32x32x16_bf16 v[32:47], v[200:203], v[88:91], v[32:47]
	s_waitcnt lgkmcnt(4)
	v_mfma_f32_32x32x16_bf16 v[48:63], v[204:207], v[88:91], v[48:63]
	ds_read_b128 v[192:195], v170 offset:160
	ds_read_b128 v[196:199], v170 offset:6816
	s_waitcnt lgkmcnt(5)
	v_mfma_f32_32x32x16_bf16 v[32:47], v[208:211], v[92:95], v[32:47]
	s_waitcnt lgkmcnt(4)
	v_mfma_f32_32x32x16_bf16 v[48:63], v[212:215], v[92:95], v[48:63]
	ds_read_b64_tr_b16 v[148:149], v171 offset:49152
	ds_read_b64_tr_b16 v[150:151], v171 offset:51200
	ds_read_b64_tr_b16 v[152:153], v171 offset:53248
	ds_read_b64_tr_b16 v[154:155], v171 offset:55296
	s_waitcnt lgkmcnt(7)
	v_mfma_f32_32x32x16_bf16 v[32:47], v[184:187], v[96:99], v[32:47]
	s_waitcnt lgkmcnt(6)
	v_mfma_f32_32x32x16_bf16 v[48:63], v[188:191], v[96:99], v[48:63]
	ds_read_b64_tr_b16 v[156:157], v171 offset:57344
	ds_read_b64_tr_b16 v[158:159], v171 offset:59392
	ds_read_b64_tr_b16 v[216:217], v171 offset:61440
	ds_read_b64_tr_b16 v[218:219], v171 offset:63488
	s_waitcnt lgkmcnt(9)
	v_mfma_f32_32x32x16_bf16 v[32:47], v[192:195], v[100:103], v[32:47]
	s_waitcnt lgkmcnt(8)
	v_mfma_f32_32x32x16_bf16 v[48:63], v[196:199], v[100:103], v[48:63]
	ds_read_b64_tr_b16 v[220:221], v171 offset:49664
	ds_read_b64_tr_b16 v[222:223], v171 offset:51712
	ds_read_b64_tr_b16 v[224:225], v171 offset:53760
	ds_read_b64_tr_b16 v[226:227], v171 offset:55808
	s_waitcnt lgkmcnt(10)
	v_mfma_f32_32x32x16_bf16 v[0:15], v[104:107], v[148:151], v[0:15]
	s_waitcnt lgkmcnt(8)
	v_mfma_f32_32x32x16_bf16 v[0:15], v[108:111], v[152:155], v[0:15]
	ds_read_b64_tr_b16 v[236:237], v171 offset:57856
	ds_read_b64_tr_b16 v[238:239], v171 offset:59904
	ds_read_b64_tr_b16 v[240:241], v171 offset:61952
	ds_read_b64_tr_b16 v[242:243], v171 offset:64000
	s_waitcnt lgkmcnt(10)
	v_mfma_f32_32x32x16_bf16 v[0:15], v[112:115], v[156:159], v[0:15]
	s_waitcnt lgkmcnt(8)
	v_mfma_f32_32x32x16_bf16 v[0:15], v[116:119], v[216:219], v[0:15]
	s_waitcnt lgkmcnt(6)
	v_mfma_f32_32x32x16_bf16 v[16:31], v[104:107], v[220:223], v[16:31]
	s_waitcnt lgkmcnt(4)
	v_mfma_f32_32x32x16_bf16 v[16:31], v[108:111], v[224:227], v[16:31]
	s_waitcnt lgkmcnt(2)
	v_mfma_f32_32x32x16_bf16 v[16:31], v[112:115], v[236:239], v[16:31]
	s_waitcnt lgkmcnt(0)
	v_mfma_f32_32x32x16_bf16 v[16:31], v[116:119], v[240:243], v[16:31]
	s_barrier
	s_waitcnt vmcnt(0)
	s_add_i32 m0, s41, 0x19c00
	s_cmp_lt_u32 s14, 5
	global_load_lds_dwordx4 v246, s[86:87]
	v_add_u32_e32 v246, v248, v246
	s_cbranch_scc0 .Lat_kd8
	s_add_i32 m0, s30, 0x19c00
	s_nop 0
	global_load_lds_dwordx4 v250, s[86:87]

; #define SBAR() __builtin_amdgcn_sched_barrier(0)
; #define SLOAD(i, k0) do { sr_[i].vs = *(const bf16x8*)(Kh + (size_t)((k0) + skey) * 2048 + 64 + sc8); \
;     sr_[i].ks = *(const bf16x8*)(Kh + (size_t)((k0) + skey) * 2048 + sc8); \
;     sr_[i].ps = *(const bf16x8*)(Kp + (size_t)((k0) + pkey) * 32 + pc8); } while (0)
; #define SWRITE(bb, i) do { *(bf16x8*)(V_lds + (bb) * AT_SHMV + vst) = sr_[i].vs; \
;     *(bf16x8*)(K_lds + (bb) * AT_SHMK + kst) = sr_[i].ks; \
;     *(bf16x8*)(K_lds + (bb) * AT_SHMK + pst) = sr_[i].ps; } while (0)
; #define SWAIT() asm volatile("s_waitcnt vmcnt(3)" ::: "memory")
; __device__ void phase_attn(const Params& p, char* lds) {
;     ...
;   for (int it = slot; it < nitems / 8; it += per) {
;     const int pair = (it >> 5) * 8 + xcd, qblk = it & 31;
;     const int b = pair >> 4, h = pair & 15;
;     const size_t row0 = (size_t)b * TL;
;     const size_t qrow = row0 + qblk * 256 + wid * 32 + r32;
;     const bf16_t* Kh = KVg + row0 * 2048 + h * 128;
;     const bf16_t* Kp = KPg + row0 * 32;
;     ...
;     for (int j = 1; j + 1 < NT; j += 2) {
;       SBAR(); at_qkt(pB0, pB1, K_lds + AT_SHMK, qr, r32, hi, -m_reg);
;       at_finishSM(pA0, pA1, alA, l_reg, pa0, pa1, pa2, pa3); SBAR();
;       SLOAD(1, (j + 2) * 64); SBAR();
;       pv_d0(o, vb0, pa0, pa1, pa2, pa3); at_partialSM(pB0, pB1, m_reg, alB, false);
;       __syncthreads(); SWAIT(); SWRITE(0, 0);
;       RESC(alB); __syncthreads();
;       SBAR(); at_qkt(pA0, pA1, K_lds, qr, r32, hi, -m_reg);
;       at_finishSM(pB0, pB1, alB, l_reg, pa0, pa1, pa2, pa3); SBAR();
;       if (j + 3 < NT) SLOAD(0, (j + 3) * 64); SBAR();
;       pv_d0(o, vb0 + AT_SHMV, pa0, pa1, pa2, pa3); at_partialSM(pA0, pA1, m_reg, alA, false);
;       __syncthreads(); SWAIT(); SWRITE(1, 1);
;       RESC(alA); __syncthreads();
;     }
;     SBAR(); at_qkt(pB0, pB1, K_lds + AT_SHMK, qr, r32, hi, -m_reg);
;     at_finishSM(pA0, pA1, alA, l_reg, pa0, pa1, pa2, pa3); SBAR();
;     pv_d0(o, vb0, pa0, pa1, pa2, pa3); at_partialSM(pB0, pB1, m_reg, alB, false);
;     __syncthreads(); RESC(alB);
;     at_finishSM(pB0, pB1, alB, l_reg, pa0, pa1, pa2, pa3); SBAR();
;     pv_d0(o, vb0 + AT_SHMV, pa0, pa1, pa2, pa3);
.Lat_rare3_back:
	v_add_f32_e32 v173, v173, v175
	v_cvt_pk_bf16_f32 v104, v32, v33
	v_cvt_pk_bf16_f32 v105, v34, v35
	v_cvt_pk_bf16_f32 v106, v36, v37
	v_cvt_pk_bf16_f32 v107, v38, v39
	v_cvt_pk_bf16_f32 v108, v40, v41
	v_cvt_pk_bf16_f32 v109, v42, v43
	v_cvt_pk_bf16_f32 v110, v44, v45
	v_cvt_pk_bf16_f32 v111, v46, v47
	v_cvt_pk_bf16_f32 v112, v48, v49
	v_cvt_pk_bf16_f32 v113, v50, v51
	v_cvt_pk_bf16_f32 v114, v52, v53
	v_cvt_pk_bf16_f32 v115, v54, v55
	v_cvt_pk_bf16_f32 v116, v56, v57
	v_cvt_pk_bf16_f32 v117, v58, v59
	v_cvt_pk_bf16_f32 v118, v60, v61
	v_cvt_pk_bf16_f32 v119, v62, v63
	ds_read_b128 v[184:187], v170 offset:13312
	ds_read_b128 v[188:191], v170 offset:19968
	ds_read_b128 v[192:195], v170 offset:13344
	ds_read_b128 v[196:199], v170 offset:20000
	s_barrier
	s_sub_u32 s13, s13, 1
	s_cmp_lg_u32 s13, 0
	s_cbranch_scc1 .Lat_loop
	ds_read_b128 v[200:203], v170 offset:13376
	ds_read_b128 v[204:207], v170 offset:20032
	s_waitcnt lgkmcnt(5)
	v_mfma_f32_32x32x16_bf16 v[32:47], v[184:187], v[80:83], v[64:79]
	s_waitcnt lgkmcnt(4)
	v_mfma_f32_32x32x16_bf16 v[48:63], v[188:191], v[80:83], v[64:79]
	ds_read_b128 v[208:211], v170 offset:13408
	ds_read_b128 v[212:215], v170 offset:20064
	s_waitcnt lgkmcnt(5)
	v_mfma_f32_32x32x16_bf16 v[32:47], v[192:195], v[84:87], v[32:47]
	s_waitcnt lgkmcnt(4)
	v_mfma_f32_32x32x16_bf16 v[48:63], v[196:199], v[84:87], v[48:63]
	ds_read_b128 v[184:187], v170 offset:13440
	ds_read_b128 v[188:191], v170 offset:20096
	s_waitcnt lgkmcnt(5)
	v_mfma_f32_32x32x16_bf16 v[32:47], v[200:203], v[88:91], v[32:47]
	s_waitcnt lgkmcnt(4)
	v_mfma_f32_32x32x16_bf16 v[48:63], v[204:207], v[88:91], v[48:63]
	ds_read_b128 v[192:195], v170 offset:13472
	ds_read_b128 v[196:199], v170 offset:20128
	s_waitcnt lgkmcnt(5)
	v_mfma_f32_32x32x16_bf16 v[32:47], v[208:211], v[92:95], v[32:47]
	s_waitcnt lgkmcnt(4)
	v_mfma_f32_32x32x16_bf16 v[48:63], v[212:215], v[92:95], v[48:63]
	ds_read_b64_tr_b16 v[148:149], v171 offset:0
	ds_read_b64_tr_b16 v[150:151], v171 offset:2048
	ds_read_b64_tr_b16 v[152:153], v171 offset:4096
	ds_read_b64_tr_b16 v[154:155], v171 offset:6144
	s_waitcnt lgkmcnt(7)
	v_mfma_f32_32x32x16_bf16 v[32:47], v[184:187], v[96:99], v[32:47]
	s_waitcnt lgkmcnt(6)
	v_mfma_f32_32x32x16_bf16 v[48:63], v[188:191], v[96:99], v[48:63]
	ds_read_b64_tr_b16 v[156:157], v171 offset:8192
	ds_read_b64_tr_b16 v[158:159], v171 offset:10240
	ds_read_b64_tr_b16 v[216:217], v171 offset:12288
	ds_read_b64_tr_b16 v[218:219], v171 offset:14336
	s_waitcnt lgkmcnt(9)
	v_mfma_f32_32x32x16_bf16 v[32:47], v[192:195], v[100:103], v[32:47]
	s_waitcnt lgkmcnt(8)
	v_mfma_f32_32x32x16_bf16 v[48:63], v[196:199], v[100:103], v[48:63]
	ds_read_b64_tr_b16 v[220:221], v171 offset:512
	ds_read_b64_tr_b16 v[222:223], v171 offset:2560
	ds_read_b64_tr_b16 v[224:225], v171 offset:4608
	ds_read_b64_tr_b16 v[226:227], v171 offset:6656
	s_waitcnt lgkmcnt(10)
	v_mfma_f32_32x32x16_bf16 v[0:15], v[104:107], v[148:151], v[0:15]
	s_waitcnt lgkmcnt(8)
	v_mfma_f32_32x32x16_bf16 v[0:15], v[108:111], v[152:155], v[0:15]
	ds_read_b64_tr_b16 v[236:237], v171 offset:8704
	ds_read_b64_tr_b16 v[238:239], v171 offset:10752
	ds_read_b64_tr_b16 v[240:241], v171 offset:12800
	ds_read_b64_tr_b16 v[242:243], v171 offset:14848
	s_waitcnt lgkmcnt(10)
	v_mfma_f32_32x32x16_bf16 v[0:15], v[112:115], v[156:159], v[0:15]
	s_waitcnt lgkmcnt(8)
	v_mfma_f32_32x32x16_bf16 v[0:15], v[116:119], v[216:219], v[0:15]
	s_waitcnt lgkmcnt(6)
	v_mfma_f32_32x32x16_bf16 v[16:31], v[104:107], v[220:223], v[16:31]
	s_waitcnt lgkmcnt(4)
	v_mfma_f32_32x32x16_bf16 v[16:31], v[108:111], v[224:227], v[16:31]
	s_waitcnt lgkmcnt(2)
	v_mfma_f32_32x32x16_bf16 v[16:31], v[112:115], v[236:239], v[16:31]
	s_waitcnt lgkmcnt(0)
	v_mfma_f32_32x32x16_bf16 v[16:31], v[116:119], v[240:243], v[16:31]
	s_barrier
	s_add_i32 s19, s12, s33
	s_lshr_b32 s16, s19, 5
	s_lshl_b32 s16, s16, 3
	s_add_i32 s16, s16, s43
	s_lshr_b32 s22, s16, 4
	s_and_b32 s21, s16, 15
	s_mul_i32 s17, s22, 0x2100000
	s_lshl_b32 s18, s21, 8
	s_add_i32 s17, s17, s18
	s_add_u32 s17, s17, 0x29400000
	s_mov_b32 s0, s17
	s_add_u32 s4, s86, s17
	s_addc_u32 s5, s87, 0
	s_mul_i32 s17, s22, 0x84000
	s_add_u32 s17, s17, 0x1de80000
	s_mov_b32 s1, s17
	s_add_u32 s6, s86, s17
	s_addc_u32 s7, s87, 0
	v_mov_b32_e32 v230, s1
	v_mov_b32_e32 v246, s0
	v_cndmask_b32_e64 v246, v246, v230, s[44:45]
	v_add_u32_e32 v246, v249, v246
	v_mov_b32_e32 v250, s0
	v_cndmask_b32_e64 v250, v250, v230, s[46:47]
	v_add_u32_e32 v250, v253, v250
	s_waitcnt vmcnt(0)
	s_add_i32 m0, s41, 0x10000
	s_cmp_lt_u32 s14, 5
	global_load_lds_dwordx4 v246, s[86:87]
	v_add_u32_e32 v246, v248, v246
	s_cbranch_scc0 .Lat_kd9
	s_add_i32 m0, s30, 0x10000
	s_nop 0
	global_load_lds_dwordx4 v250, s[86:87]

; #define SBAR() __builtin_amdgcn_sched_barrier(0)
; #define SLOAD(i, k0) do { sr_[i].vs = *(const bf16x8*)(Kh + (size_t)((k0) + skey) * 2048 + 64 + sc8); \
;     sr_[i].ks = *(const bf16x8*)(Kh + (size_t)((k0) + skey) * 2048 + sc8); \
;     sr_[i].ps = *(const bf16x8*)(Kp + (size_t)((k0) + pkey) * 32 + pc8); } while (0)
; #define SWRITE(bb, i) do { *(bf16x8*)(V_lds + (bb) * AT_SHMV + vst) = sr_[i].vs; \
;     *(bf16x8*)(K_lds + (bb) * AT_SHMK + kst) = sr_[i].ks; \
;     *(bf16x8*)(K_lds + (bb) * AT_SHMK + pst) = sr_[i].ps; } while (0)
; #define SWAIT() asm volatile("s_waitcnt vmcnt(3)" ::: "memory")
; #define RESC(a) do { if (__any((a) < 1.f)) { if (hi == 0) al_l[r32] = (a); asm volatile("s_waitcnt lgkmcnt(0)" ::: "memory"); \
;     _Pragma("unroll") for (int dd = 0; dd < 2; ++dd) _Pragma("unroll") for (int r = 0; r < 16; ++r) o[dd][r] *= al_l[crow(r, hi)]; } } while (0)
; __device__ void phase_attn(const Params& p, char* lds) {
;     ...
;       SBAR(); at_qkt(pA0, pA1, K_lds, qr, r32, hi, -m_reg);
;       at_finishSM(pB0, pB1, alB, l_reg, pa0, pa1, pa2, pa3); SBAR();
;       if (j + 3 < NT) SLOAD(0, (j + 3) * 64); SBAR();
;       pv_d0(o, vb0 + AT_SHMV, pa0, pa1, pa2, pa3); at_partialSM(pA0, pA1, m_reg, alA, false);
;       __syncthreads(); SWAIT(); SWRITE(1, 1);
;       RESC(alA); __syncthreads();
;     }
;     SBAR(); at_qkt(pB0, pB1, K_lds + AT_SHMK, qr, r32, hi, -m_reg);
;     at_finishSM(pA0, pA1, alA, l_reg, pa0, pa1, pa2, pa3); SBAR();
;     pv_d0(o, vb0, pa0, pa1, pa2, pa3); at_partialSM(pB0, pB1, m_reg, alB, false);
;     __syncthreads(); RESC(alB);
;     at_finishSM(pB0, pB1, alB, l_reg, pa0, pa1, pa2, pa3); SBAR();
;     pv_d0(o, vb0 + AT_SHMV, pa0, pa1, pa2, pa3);
.Lat_rare_t129_back:
	v_add_f32_e32 v173, v173, v175
	v_cvt_pk_bf16_f32 v104, v32, v33
	v_cvt_pk_bf16_f32 v105, v34, v35
	v_cvt_pk_bf16_f32 v106, v36, v37
	v_cvt_pk_bf16_f32 v107, v38, v39
	v_cvt_pk_bf16_f32 v108, v40, v41
	v_cvt_pk_bf16_f32 v109, v42, v43
	v_cvt_pk_bf16_f32 v110, v44, v45
	v_cvt_pk_bf16_f32 v111, v46, v47
	v_cvt_pk_bf16_f32 v112, v48, v49
	v_cvt_pk_bf16_f32 v113, v50, v51
	v_cvt_pk_bf16_f32 v114, v52, v53
	v_cvt_pk_bf16_f32 v115, v54, v55
	v_cvt_pk_bf16_f32 v116, v56, v57
	v_cvt_pk_bf16_f32 v117, v58, v59
	v_cvt_pk_bf16_f32 v118, v60, v61
	v_cvt_pk_bf16_f32 v119, v62, v63
	ds_read_b128 v[184:187], v170 offset:26624
	ds_read_b128 v[188:191], v170 offset:33280
	ds_read_b128 v[192:195], v170 offset:26656
	ds_read_b128 v[196:199], v170 offset:33312
	s_barrier
	ds_read_b128 v[200:203], v170 offset:26688
	ds_read_b128 v[204:207], v170 offset:33344
	s_waitcnt lgkmcnt(5)
	v_mfma_f32_32x32x16_bf16 v[32:47], v[184:187], v[80:83], v[64:79]
	s_waitcnt lgkmcnt(4)
	v_mfma_f32_32x32x16_bf16 v[48:63], v[188:191], v[80:83], v[64:79]
	ds_read_b128 v[208:211], v170 offset:26720
	ds_read_b128 v[212:215], v170 offset:33376
	s_waitcnt lgkmcnt(5)
	v_mfma_f32_32x32x16_bf16 v[32:47], v[192:195], v[84:87], v[32:47]
	s_waitcnt lgkmcnt(4)
	v_mfma_f32_32x32x16_bf16 v[48:63], v[196:199], v[84:87], v[48:63]
	ds_read_b128 v[184:187], v170 offset:26752
	ds_read_b128 v[188:191], v170 offset:33408
	s_waitcnt lgkmcnt(5)
	v_mfma_f32_32x32x16_bf16 v[32:47], v[200:203], v[88:91], v[32:47]
	s_waitcnt lgkmcnt(4)
	v_mfma_f32_32x32x16_bf16 v[48:63], v[204:207], v[88:91], v[48:63]
	ds_read_b128 v[192:195], v170 offset:26784
	ds_read_b128 v[196:199], v170 offset:33440
	s_waitcnt lgkmcnt(5)
	v_mfma_f32_32x32x16_bf16 v[32:47], v[208:211], v[92:95], v[32:47]
	s_waitcnt lgkmcnt(4)
	v_mfma_f32_32x32x16_bf16 v[48:63], v[212:215], v[92:95], v[48:63]
	ds_read_b64_tr_b16 v[148:149], v171 offset:16384
	ds_read_b64_tr_b16 v[150:151], v171 offset:18432
	ds_read_b64_tr_b16 v[152:153], v171 offset:20480
	ds_read_b64_tr_b16 v[154:155], v171 offset:22528
	s_waitcnt lgkmcnt(7)
	v_mfma_f32_32x32x16_bf16 v[32:47], v[184:187], v[96:99], v[32:47]
	s_waitcnt lgkmcnt(6)
	v_mfma_f32_32x32x16_bf16 v[48:63], v[188:191], v[96:99], v[48:63]
	ds_read_b64_tr_b16 v[156:157], v171 offset:24576
	ds_read_b64_tr_b16 v[158:159], v171 offset:26624
	ds_read_b64_tr_b16 v[216:217], v171 offset:28672
	ds_read_b64_tr_b16 v[218:219], v171 offset:30720
	s_waitcnt lgkmcnt(9)
	v_mfma_f32_32x32x16_bf16 v[32:47], v[192:195], v[100:103], v[32:47]
	s_waitcnt lgkmcnt(8)
	v_mfma_f32_32x32x16_bf16 v[48:63], v[196:199], v[100:103], v[48:63]
	ds_read_b64_tr_b16 v[220:221], v171 offset:16896
	ds_read_b64_tr_b16 v[222:223], v171 offset:18944
	ds_read_b64_tr_b16 v[224:225], v171 offset:20992
	ds_read_b64_tr_b16 v[226:227], v171 offset:23040
	s_waitcnt lgkmcnt(10)
	v_mfma_f32_32x32x16_bf16 v[0:15], v[104:107], v[148:151], v[0:15]
	s_waitcnt lgkmcnt(8)
	v_mfma_f32_32x32x16_bf16 v[0:15], v[108:111], v[152:155], v[0:15]
	ds_read_b64_tr_b16 v[236:237], v171 offset:25088
	ds_read_b64_tr_b16 v[238:239], v171 offset:27136
	ds_read_b64_tr_b16 v[240:241], v171 offset:29184
	ds_read_b64_tr_b16 v[242:243], v171 offset:31232
	s_waitcnt lgkmcnt(10)
	v_mfma_f32_32x32x16_bf16 v[0:15], v[112:115], v[156:159], v[0:15]
	s_waitcnt lgkmcnt(8)
	v_mfma_f32_32x32x16_bf16 v[0:15], v[116:119], v[216:219], v[0:15]
	s_waitcnt lgkmcnt(6)
	v_mfma_f32_32x32x16_bf16 v[16:31], v[104:107], v[220:223], v[16:31]
	s_waitcnt lgkmcnt(4)
	v_mfma_f32_32x32x16_bf16 v[16:31], v[108:111], v[224:227], v[16:31]
	s_waitcnt lgkmcnt(2)
	v_mfma_f32_32x32x16_bf16 v[16:31], v[112:115], v[236:239], v[16:31]
	s_waitcnt lgkmcnt(0)
	v_mfma_f32_32x32x16_bf16 v[16:31], v[116:119], v[240:243], v[16:31]
	s_barrier
	s_mov_b64 s[36:37], s[4:5]
	s_waitcnt vmcnt(0)
	s_add_i32 m0, s41, 0x13400
	s_cmp_lt_u32 s14, 5
	global_load_lds_dwordx4 v246, s[86:87]
	v_add_u32_e32 v246, v248, v246
	s_cbranch_scc0 .Lat_kd10
	s_add_i32 m0, s30, 0x13400
	s_nop 0
	global_load_lds_dwordx4 v250, s[86:87]

; __device__ __forceinline__ int crow(int r, int hi) { return (r & 3) + 8 * (r >> 2) + 4 * hi; }
; #define SBAR() __builtin_amdgcn_sched_barrier(0)
; #define SLOAD(i, k0) do { sr_[i].vs = *(const bf16x8*)(Kh + (size_t)((k0) + skey) * 2048 + 64 + sc8); \
;     sr_[i].ks = *(const bf16x8*)(Kh + (size_t)((k0) + skey) * 2048 + sc8); \
;     sr_[i].ps = *(const bf16x8*)(Kp + (size_t)((k0) + pkey) * 32 + pc8); } while (0)
; #define SWRITE(bb, i) do { *(bf16x8*)(V_lds + (bb) * AT_SHMV + vst) = sr_[i].vs; \
;     *(bf16x8*)(K_lds + (bb) * AT_SHMK + kst) = sr_[i].ks; \
;     *(bf16x8*)(K_lds + (bb) * AT_SHMK + pst) = sr_[i].ps; } while (0)
; #define SWAIT() asm volatile("s_waitcnt vmcnt(3)" ::: "memory")
; #define RESC(a) do { if (__any((a) < 1.f)) { if (hi == 0) al_l[r32] = (a); asm volatile("s_waitcnt lgkmcnt(0)" ::: "memory"); \
;     _Pragma("unroll") for (int dd = 0; dd < 2; ++dd) _Pragma("unroll") for (int r = 0; r < 16; ++r) o[dd][r] *= al_l[crow(r, hi)]; } } while (0)
; __device__ void phase_attn(const Params& p, char* lds) {
;     ...
;       SBAR(); at_qkt(pA0, pA1, K_lds, qr, r32, hi, -m_reg);
;       at_finishSM(pB0, pB1, alB, l_reg, pa0, pa1, pa2, pa3); SBAR();
;       if (j + 3 < NT) SLOAD(0, (j + 3) * 64); SBAR();
;       pv_d0(o, vb0 + AT_SHMV, pa0, pa1, pa2, pa3); at_partialSM(pA0, pA1, m_reg, alA, false);
;       __syncthreads(); SWAIT(); SWRITE(1, 1);
;       RESC(alA); __syncthreads();
;     }
;     SBAR(); at_qkt(pB0, pB1, K_lds + AT_SHMK, qr, r32, hi, -m_reg);
;     at_finishSM(pA0, pA1, alA, l_reg, pa0, pa1, pa2, pa3); SBAR();
;     pv_d0(o, vb0, pa0, pa1, pa2, pa3); at_partialSM(pB0, pB1, m_reg, alB, false);
;     __syncthreads(); RESC(alB);
;     at_finishSM(pB0, pB1, alB, l_reg, pa0, pa1, pa2, pa3); SBAR();
;     pv_d0(o, vb0 + AT_SHMV, pa0, pa1, pa2, pa3);
;     if (hi == 0) li_l[r32] = l_reg;
;     asm volatile("s_waitcnt lgkmcnt(0)" ::: "memory");
;     float rli[16];
; #pragma unroll
;     for (int r = 0; r < 16; ++r) rli[r] = __builtin_amdgcn_rcpf(li_l[crow(r, hi)]);
;     bf16_t* Gw = G1 + (row0 + qblk * 256 + wid * 32) * 1024 + h * 64 + r32;
;     bf16_t gin[32];
; #pragma unroll
;     for (int r = 0; r < 16; ++r) { gin[2 * r] = Gw[(size_t)crow(r, hi) * 1024]; gin[2 * r + 1] = Gw[(size_t)crow(r, hi) * 1024 + 32]; }
.Lat_rare_t130_back:
	v_add_f32_e32 v173, v173, v175
	v_cvt_pk_bf16_f32 v104, v32, v33
	v_cvt_pk_bf16_f32 v105, v34, v35
	v_cvt_pk_bf16_f32 v106, v36, v37
	v_cvt_pk_bf16_f32 v107, v38, v39
	v_cvt_pk_bf16_f32 v108, v40, v41
	v_cvt_pk_bf16_f32 v109, v42, v43
	v_cvt_pk_bf16_f32 v110, v44, v45
	v_cvt_pk_bf16_f32 v111, v46, v47
	v_cvt_pk_bf16_f32 v112, v48, v49
	v_cvt_pk_bf16_f32 v113, v50, v51
	v_cvt_pk_bf16_f32 v114, v52, v53
	v_cvt_pk_bf16_f32 v115, v54, v55
	v_cvt_pk_bf16_f32 v116, v56, v57
	v_cvt_pk_bf16_f32 v117, v58, v59
	v_cvt_pk_bf16_f32 v118, v60, v61
	v_cvt_pk_bf16_f32 v119, v62, v63
	ds_read_b128 v[184:187], v170 offset:39936
	ds_read_b128 v[188:191], v170 offset:46592
	ds_read_b128 v[192:195], v170 offset:39968
	ds_read_b128 v[196:199], v170 offset:46624
	s_barrier
	ds_read_b128 v[200:203], v170 offset:40000
	ds_read_b128 v[204:207], v170 offset:46656
	s_waitcnt lgkmcnt(5)
	v_mfma_f32_32x32x16_bf16 v[32:47], v[184:187], v[80:83], v[64:79]
	s_waitcnt lgkmcnt(4)
	v_mfma_f32_32x32x16_bf16 v[48:63], v[188:191], v[80:83], v[64:79]
	ds_read_b128 v[208:211], v170 offset:40032
	ds_read_b128 v[212:215], v170 offset:46688
	s_waitcnt lgkmcnt(5)
	v_mfma_f32_32x32x16_bf16 v[32:47], v[192:195], v[84:87], v[32:47]
	s_waitcnt lgkmcnt(4)
	v_mfma_f32_32x32x16_bf16 v[48:63], v[196:199], v[84:87], v[48:63]
	ds_read_b128 v[184:187], v170 offset:40064
	ds_read_b128 v[188:191], v170 offset:46720
	s_waitcnt lgkmcnt(5)
	v_mfma_f32_32x32x16_bf16 v[32:47], v[200:203], v[88:91], v[32:47]
	s_waitcnt lgkmcnt(4)
	v_mfma_f32_32x32x16_bf16 v[48:63], v[204:207], v[88:91], v[48:63]
	ds_read_b128 v[192:195], v170 offset:40096
	ds_read_b128 v[196:199], v170 offset:46752
	s_waitcnt lgkmcnt(5)
	v_mfma_f32_32x32x16_bf16 v[32:47], v[208:211], v[92:95], v[32:47]
	s_waitcnt lgkmcnt(4)
	v_mfma_f32_32x32x16_bf16 v[48:63], v[212:215], v[92:95], v[48:63]
	ds_read_b64_tr_b16 v[148:149], v171 offset:32768
	ds_read_b64_tr_b16 v[150:151], v171 offset:34816
	ds_read_b64_tr_b16 v[152:153], v171 offset:36864
	ds_read_b64_tr_b16 v[154:155], v171 offset:38912
	s_waitcnt lgkmcnt(7)
	v_mfma_f32_32x32x16_bf16 v[32:47], v[184:187], v[96:99], v[32:47]
	s_waitcnt lgkmcnt(6)
	v_mfma_f32_32x32x16_bf16 v[48:63], v[188:191], v[96:99], v[48:63]
	ds_read_b64_tr_b16 v[156:157], v171 offset:40960
	ds_read_b64_tr_b16 v[158:159], v171 offset:43008
	ds_read_b64_tr_b16 v[216:217], v171 offset:45056
	ds_read_b64_tr_b16 v[218:219], v171 offset:47104
	s_waitcnt lgkmcnt(9)
	v_mfma_f32_32x32x16_bf16 v[32:47], v[192:195], v[100:103], v[32:47]
	s_waitcnt lgkmcnt(8)
	v_mfma_f32_32x32x16_bf16 v[48:63], v[196:199], v[100:103], v[48:63]
	ds_read_b64_tr_b16 v[220:221], v171 offset:33280
	ds_read_b64_tr_b16 v[222:223], v171 offset:35328
	ds_read_b64_tr_b16 v[224:225], v171 offset:37376
	ds_read_b64_tr_b16 v[226:227], v171 offset:39424
	s_waitcnt lgkmcnt(10)
	v_mfma_f32_32x32x16_bf16 v[0:15], v[104:107], v[148:151], v[0:15]
	s_waitcnt lgkmcnt(8)
	v_mfma_f32_32x32x16_bf16 v[0:15], v[108:111], v[152:155], v[0:15]
	ds_read_b64_tr_b16 v[236:237], v171 offset:41472
	ds_read_b64_tr_b16 v[238:239], v171 offset:43520
	ds_read_b64_tr_b16 v[240:241], v171 offset:45568
	ds_read_b64_tr_b16 v[242:243], v171 offset:47616
	s_waitcnt lgkmcnt(10)
	v_mfma_f32_32x32x16_bf16 v[0:15], v[112:115], v[156:159], v[0:15]
	s_waitcnt lgkmcnt(8)
	v_mfma_f32_32x32x16_bf16 v[0:15], v[116:119], v[216:219], v[0:15]
	s_waitcnt lgkmcnt(6)
	v_mfma_f32_32x32x16_bf16 v[16:31], v[104:107], v[220:223], v[16:31]
	s_waitcnt lgkmcnt(4)
	v_mfma_f32_32x32x16_bf16 v[16:31], v[108:111], v[224:227], v[16:31]
	s_waitcnt lgkmcnt(2)
	v_mfma_f32_32x32x16_bf16 v[16:31], v[112:115], v[236:239], v[16:31]
	s_waitcnt lgkmcnt(0)
	v_mfma_f32_32x32x16_bf16 v[16:31], v[116:119], v[240:243], v[16:31]
	s_barrier
	s_add_u32 s8, s28, 0x0
	s_addc_u32 s9, s29, 0
	global_load_ushort v120, v235, s[8:9] offset:0
	global_load_ushort v121, v235, s[8:9] offset:64
	global_load_ushort v122, v235, s[8:9] offset:2048
	global_load_ushort v123, v235, s[8:9] offset:2112
	s_add_u32 s8, s28, 0x1000
	s_addc_u32 s9, s29, 0
	global_load_ushort v124, v235, s[8:9] offset:0
	global_load_ushort v125, v235, s[8:9] offset:64
	global_load_ushort v126, v235, s[8:9] offset:2048
	global_load_ushort v127, v235, s[8:9] offset:2112
	s_add_u32 s8, s28, 0x4000
	s_addc_u32 s9, s29, 0
	global_load_ushort v132, v235, s[8:9] offset:0
	global_load_ushort v133, v235, s[8:9] offset:64
	global_load_ushort v134, v235, s[8:9] offset:2048
	global_load_ushort v135, v235, s[8:9] offset:2112
	s_add_u32 s8, s28, 0x5000
	s_addc_u32 s9, s29, 0
	global_load_ushort v136, v235, s[8:9] offset:0
	global_load_ushort v137, v235, s[8:9] offset:64
	global_load_ushort v138, v235, s[8:9] offset:2048
	global_load_ushort v139, v235, s[8:9] offset:2112
	s_add_u32 s8, s28, 0x8000
	s_addc_u32 s9, s29, 0
	global_load_ushort v140, v235, s[8:9] offset:0
	global_load_ushort v141, v235, s[8:9] offset:64
	global_load_ushort v142, v235, s[8:9] offset:2048
	global_load_ushort v143, v235, s[8:9] offset:2112
	s_add_u32 s8, s28, 0x9000
	s_addc_u32 s9, s29, 0
	global_load_ushort v144, v235, s[8:9] offset:0
	global_load_ushort v145, v235, s[8:9] offset:64
	global_load_ushort v146, v235, s[8:9] offset:2048
	global_load_ushort v147, v235, s[8:9] offset:2112
	s_add_u32 s8, s28, 0xc000
	s_addc_u32 s9, s29, 0
	global_load_ushort v200, v235, s[8:9] offset:0
	global_load_ushort v201, v235, s[8:9] offset:64
	global_load_ushort v202, v235, s[8:9] offset:2048
	global_load_ushort v203, v235, s[8:9] offset:2112
	s_add_u32 s8, s28, 0xd000
	s_addc_u32 s9, s29, 0
	global_load_ushort v204, v235, s[8:9] offset:0
	global_load_ushort v205, v235, s[8:9] offset:64
	global_load_ushort v206, v235, s[8:9] offset:2048
	global_load_ushort v207, v235, s[8:9] offset:2112
	s_waitcnt vmcnt(32)
	s_add_i32 m0, s41, 0x16800
	s_cmp_lt_u32 s14, 5
	global_load_lds_dwordx4 v246, s[86:87]
	v_add_u32_e32 v246, v248, v246
	s_cbranch_scc0 .Lat_kd11
	s_add_i32 m0, s30, 0x16800
	s_nop 0
	global_load_lds_dwordx4 v250, s[86:87]
